# ffn2 K-rotation with 512B per m-tile skew (krot sh9)
# baseline (speedup 1.0000x reference)
.LBB0_126:
	s_lshr_b32 s15, s14, 3
	v_mov_b32_e32 v6, v254
	s_and_b32 s16, s15, 0xffffff8
	s_and_b32 s15, s14, 7
	v_ashrrev_i32_e32 v0, 3, v6
	s_lshl_b32 s83, s16, 7
	s_lshl_b32 s14, s14, 4
	v_xor_b32_e32 v5, v0, v6
	s_sub_i32 s14, s14, s83
	v_lshlrev_b32_e32 v1, 3, v5
	s_and_b32 s22, s14, 0xffffff80
	v_and_b32_e32 v7, 56, v1
	v_ashrrev_i32_e32 v1, 31, v0
	s_or_b32 s17, s16, s15
	s_ashr_i32 s23, s22, 31
	v_lshlrev_b64 v[2:3], 12, v[0:1]
	s_lshl_b32 s26, s17, 7
	s_lshl_b64 s[36:37], s[22:23], 13
	s_mov_b64 s[16:17], -1
	s_and_b64 vcc, exec, s[40:41]
	v_lshlrev_b64 v[2:3], 1, v[2:3]
	v_lshlrev_b32_e32 v148, 1, v7
	v_lshlrev_b32_e32 v7, 4, v6
	s_cbranch_vccz .LBB0_128
	s_lshl_b64 s[16:17], s[26:27], 13
	s_add_u32 s16, s25, s16
	s_addc_u32 s17, s33, s17
	s_lshl_b32 s14, s26, 2
	s_and_b32 s14, s14, 0xe00
	s_add_u32 s16, s16, s14
	s_addc_u32 s17, s17, 0
	v_lshlrev_b32_e32 v85, 4, v6
	s_add_u32 s40, s44, s36
	v_lshl_add_u64 v[8:9], s[16:17], 0, v[2:3]
	v_readfirstlane_b32 s14, v85
	v_add_u32_e32 v14, 0x1000, v85
	s_addc_u32 s41, s45, s37
	s_lshl_b32 s84, s26, 2
	s_and_b32 s84, s84, 0xe00
	s_add_u32 s40, s40, s84
	s_addc_u32 s41, s41, 0
	v_lshl_add_u64 v[8:9], v[8:9], 0, v[148:149]
	s_mov_b32 m0, s14
	s_mov_b64 s[16:17], 0x40000
	v_readfirstlane_b32 s14, v14
	v_add_u32_e32 v14, 0x2000, v85
	v_lshl_add_u64 v[10:11], s[40:41], 0, v[2:3]
	s_barrier
	global_load_lds_dwordx4 v[8:9], off
	v_lshl_add_u64 v[12:13], v[8:9], 0, s[16:17]
	s_mov_b32 m0, s14
	s_mov_b64 s[40:41], 0x80000
	v_readfirstlane_b32 s14, v14
	global_load_lds_dwordx4 v[12:13], off
	v_lshl_add_u64 v[12:13], v[8:9], 0, s[40:41]
	s_mov_b32 m0, s14
	s_mov_b64 s[84:85], 0xc0000
	global_load_lds_dwordx4 v[12:13], off
	v_add_u32_e32 v12, 0x3000, v85
	v_lshl_add_u64 v[8:9], v[8:9], 0, s[84:85]
	v_readfirstlane_b32 s14, v12
	s_mov_b32 m0, s14
	v_add_u32_e32 v12, 0x5000, v85
	global_load_lds_dwordx4 v[8:9], off
	v_add_u32_e32 v8, 0x4000, v85
	v_lshl_add_u64 v[10:11], v[10:11], 0, v[148:149]
	v_readfirstlane_b32 s14, v8
	s_mov_b32 m0, s14
	v_readfirstlane_b32 s14, v12
	v_add_u32_e32 v12, 0x6000, v85
	global_load_lds_dwordx4 v[10:11], off
	v_lshl_add_u64 v[8:9], v[10:11], 0, s[16:17]
	s_mov_b32 m0, s14
	v_readfirstlane_b32 s14, v12
	global_load_lds_dwordx4 v[8:9], off
	v_lshl_add_u64 v[8:9], v[10:11], 0, s[40:41]
	s_mov_b32 m0, s14
	s_mov_b64 s[16:17], 0
	global_load_lds_dwordx4 v[8:9], off
	v_lshl_add_u64 v[8:9], v[10:11], 0, s[84:85]
	v_add_u32_e32 v10, 0x7000, v85
	s_nop 0
	v_readfirstlane_b32 s14, v10
	s_mov_b32 m0, s14
	s_nop 0
	global_load_lds_dwordx4 v[8:9], off

.LBB0_130:
	s_add_u32 s14, s25, s30
	v_cmp_lt_i32_e32 vcc, -1, v4
	s_addc_u32 s17, s33, s31
	s_and_b64 s[30:31], vcc, exec
	v_lshrrev_b32_e32 v7, 4, v6
	v_and_b32_e32 v9, 7, v6
	s_cselect_b32 s31, s17, 0
	s_cselect_b32 s30, s14, 0
	s_add_u32 s28, s44, s28
	v_bfe_u32 v8, v6, 4, 2
	v_bitop3_b32 v7, v7, v9, 3 bitop3:0x6c
	s_addc_u32 s29, s45, s29
	v_lshlrev_b32_e32 v86, 4, v7
	v_bitop3_b32 v7, v8, v9, 4 bitop3:0x36
	v_and_b32_e32 v4, 15, v6
	v_lshlrev_b32_e32 v87, 4, v7
	v_lshrrev_b32_e32 v7, 1, v6
	s_cmp_lg_u64 s[30:31], 0
	v_and_or_b32 v4, v7, s47, v4
	v_lshl_add_u64 v[8:9], s[30:31], 0, v[148:149]
	s_cselect_b64 s[30:31], -1, 0
	s_lshl_b32 s14, s15, 7
	v_lshlrev_b32_e32 v88, 7, v4
	v_lshlrev_b32_e32 v4, 7, v6
	s_add_i32 s14, s83, s14
	s_mov_b32 s15, s27
	v_and_b32_e32 v89, 0x2780, v4
	v_lshl_add_u64 v[6:7], s[28:29], 0, v[148:149]
	v_lshlrev_b64 v[0:1], 13, v[0:1]
	v_lshlrev_b32_e32 v4, 4, v5
	s_lshl_b64 s[14:15], s[14:15], 13
	v_lshl_add_u64 v[64:65], v[8:9], 0, v[2:3]
	v_lshl_add_u64 v[66:67], v[6:7], 0, v[2:3]
	s_and_b32 s16, s56, 7
	s_lshl_b32 s16, s16, 9
	v_mov_b32_e32 v10, s16
	v_mov_b32_e32 v11, 0
	v_lshl_add_u64 v[64:65], v[64:65], 0, v[10:11]
	v_lshl_add_u64 v[66:67], v[66:67], 0, v[10:11]
	v_lshl_add_u64 v[2:3], v[0:1], 0, s[36:37]
	v_and_b32_e32 v148, 0x70, v4
	v_lshl_add_u64 v[0:1], v[0:1], 0, s[14:15]
	s_mov_b64 s[40:41], 0x40000
	s_mov_b64 s[84:85], 0x80000
	s_mov_b64 s[86:87], 0xc0000
	v_lshl_add_u64 v[2:3], v[2:3], 0, v[148:149]
	v_or_b32_e32 v0, v0, v148
	v_mov_b32_e32 v56, 0
	s_mov_b32 s16, 0
	s_mov_b64 s[28:29], 0
	v_lshl_add_u64 v[68:69], v[64:65], 0, s[40:41]
	v_lshl_add_u64 v[70:71], v[64:65], 0, s[84:85]
	v_lshl_add_u64 v[72:73], v[64:65], 0, s[86:87]
	v_lshl_add_u64 v[74:75], v[66:67], 0, s[40:41]
	v_lshl_add_u64 v[76:77], v[66:67], 0, s[84:85]
	v_lshl_add_u64 v[78:79], v[66:67], 0, s[86:87]
	v_lshl_add_u64 v[80:81], s[10:11], 0, v[2:3]
	v_lshl_add_u64 v[82:83], s[10:11], 0, v[0:1]
	s_mov_b32 s17, 0
	v_mov_b32_e32 v57, v56
	v_mov_b32_e32 v58, v56
	v_mov_b32_e32 v59, v56
	v_mov_b32_e32 v0, v56
	v_mov_b32_e32 v1, v56
	v_mov_b32_e32 v2, v56
	v_mov_b32_e32 v3, v56
	v_mov_b32_e32 v4, v56
	v_mov_b32_e32 v5, v56
	v_mov_b32_e32 v6, v56
	v_mov_b32_e32 v7, v56
	v_mov_b32_e32 v8, v56
	v_mov_b32_e32 v9, v56
	v_mov_b32_e32 v10, v56
	v_mov_b32_e32 v11, v56
	v_mov_b32_e32 v12, v56
	v_mov_b32_e32 v13, v56
	v_mov_b32_e32 v14, v56
	v_mov_b32_e32 v15, v56
	v_mov_b32_e32 v16, v56
	v_mov_b32_e32 v17, v56
	v_mov_b32_e32 v18, v56
	v_mov_b32_e32 v19, v56
	v_mov_b32_e32 v20, v56
	v_mov_b32_e32 v21, v56
	v_mov_b32_e32 v22, v56
	v_mov_b32_e32 v23, v56
	v_mov_b32_e32 v24, v56
	v_mov_b32_e32 v25, v56
	v_mov_b32_e32 v26, v56
	v_mov_b32_e32 v27, v56
	v_mov_b32_e32 v28, v56
	v_mov_b32_e32 v29, v56
	v_mov_b32_e32 v30, v56
	v_mov_b32_e32 v31, v56
	v_mov_b32_e32 v32, v56
	v_mov_b32_e32 v33, v56
	v_mov_b32_e32 v34, v56
	v_mov_b32_e32 v35, v56
	v_mov_b32_e32 v36, v56
	v_mov_b32_e32 v37, v56
	v_mov_b32_e32 v38, v56
	v_mov_b32_e32 v39, v56
	s_waitcnt vmcnt(0)
	v_mov_b32_e32 v40, v56
	v_mov_b32_e32 v41, v56
	v_mov_b32_e32 v42, v56
	v_mov_b32_e32 v43, v56
	v_mov_b32_e32 v44, v56
	v_mov_b32_e32 v45, v56
	v_mov_b32_e32 v46, v56
	v_mov_b32_e32 v47, v56
	v_mov_b32_e32 v48, v56
	v_mov_b32_e32 v49, v56
	v_mov_b32_e32 v50, v56
	v_mov_b32_e32 v51, v56
	v_mov_b32_e32 v52, v56
	v_mov_b32_e32 v53, v56
	v_mov_b32_e32 v54, v56
	v_mov_b32_e32 v55, v56
	v_mov_b32_e32 v60, v56
	v_mov_b32_e32 v61, v56
	v_mov_b32_e32 v62, v56
	v_mov_b32_e32 v63, v56
	s_branch .LBB0_132

.LBB0_136:
	s_andn2_b64 vcc, exec, s[14:15]
	s_cbranch_vccnz .LBB0_131
	s_add_i32 s14, s16, 0x8000
	s_and_b32 s14, s14, 0x8000
	v_add_u32_e32 v94, s14, v85
	s_lshl_b32 s15, s26, 2
	s_and_b32 s15, s15, 0xe00
	v_readfirstlane_b32 s14, v94
	s_mov_b32 m0, s14
	s_add_u32 s14, s15, s28
	s_add_u32 s14, s14, 0x80
	s_and_b32 s14, s14, 0x1fff
	s_add_u32 s14, s14, 0x1201000
	s_mov_b32 s15, 0
	v_lshl_add_u64 v[92:93], v[82:83], 0, s[14:15]
	s_sub_u32 s14, s14, 0x800000
	v_lshl_add_u64 v[90:91], v[80:81], 0, s[14:15]
	global_load_lds_dwordx4 v[92:93], off
	s_add_u32 m0, m0, 0x1000
	v_lshl_add_u64 v[92:93], v[92:93], 0, s[40:41]
	global_load_lds_dwordx4 v[92:93], off
	s_add_u32 m0, m0, 0x1000
	v_lshl_add_u64 v[92:93], v[92:93], 0, s[40:41]
	global_load_lds_dwordx4 v[92:93], off
	s_add_u32 m0, m0, 0x1000
	v_lshl_add_u64 v[92:93], v[92:93], 0, s[40:41]
	global_load_lds_dwordx4 v[92:93], off
	s_add_u32 m0, m0, 0x1000
	s_nop 0
	global_load_lds_dwordx4 v[90:91], off
	s_add_u32 m0, m0, 0x1000
	v_lshl_add_u64 v[90:91], v[90:91], 0, s[40:41]
	global_load_lds_dwordx4 v[90:91], off
	s_add_u32 m0, m0, 0x1000
	v_lshl_add_u64 v[90:91], v[90:91], 0, s[40:41]
	global_load_lds_dwordx4 v[90:91], off
	s_add_u32 m0, m0, 0x1000
	v_lshl_add_u64 v[90:91], v[90:91], 0, s[40:41]
	global_load_lds_dwordx4 v[90:91], off
	s_branch .LBB0_131
